# MLA inline LDS stores moved later, into the PV section (after 15th MFMA) instead of after the 10th
# baseline (speedup 1.0000x reference)
; template <bool MLA, int DK, int DV>
; __device__ __forceinline__ void attn_core(const Params& p, int b, int h, int map, int q0, int nt, char* smem,
;                                           f32x16 (&o)[DV / 32], float& lout) {
;     ...
;         for (int i = 0; i < 16; ++i) nxt_[sub][i] = 0.f;
;       constexpr int NM = 2 * NKS;
;       bf16x8 kf[NM];
; #pragma unroll
;       for (int j = 0; j < NM; ++j) kf[j] = *(const bf16x8*)(Kn + ((j / NKS) * 32 + r) * KS_STRIDE + (j % NKS) * 16 + h2 * 8);
; #pragma unroll
;       for (int j = 0; j < NM; ++j) {
;         nxt_[j / NKS] = MFMA32(kf[j], qf[j % NKS], nxt_[j / NKS]);
; #pragma unroll
;         for (int e_ = j * 32 / NM; e_ < (j + 1) * 32 / NM; ++e_) {
;           const float x_ = __builtin_amdgcn_exp2f(fmaf(cur_[e_ >> 4][e_ & 15], sc, -mrun));
;           cur_[e_ >> 4][e_ & 15] = x_; psum += x_;
;         }
;       }
;       __builtin_amdgcn_sched_group_barrier(0x100, NM, 0);
; #pragma unroll
;       for (int j = 0; j < NM; ++j) {
;         __builtin_amdgcn_sched_group_barrier(0x008, 1, 0);
;         __builtin_amdgcn_sched_group_barrier(0x002, 96 / NM, 0);
;       }
;     } else {
; #pragma unroll
;       for (int sub = 0; sub < 2; ++sub)
; #pragma unroll
;         for (int i = 0; i < 16; ++i) { const float x_ = __builtin_amdgcn_exp2f(fmaf(cur_[sub][i], sc, -mrun)); cur_[sub][i] = x_; psum += x_; }
;     }
;     lrun += psum;
;     bf16x8 pb[4];
; #pragma unroll
;     for (int kb = 0; kb < 4; ++kb) {
;       const int sub = kb >> 1, s8 = (kb & 1) * 8;
;       u32x4 pk;
;       pk.x = pack2(cur_[sub][s8 + 0], cur_[sub][s8 + 1]);
;       pk.y = pack2(cur_[sub][s8 + 2], cur_[sub][s8 + 3]);
;       pk.z = pack2(cur_[sub][s8 + 4], cur_[sub][s8 + 5]);
;       pk.w = pack2(cur_[sub][s8 + 6], cur_[sub][s8 + 7]);
;       pb[kb] = __builtin_bit_cast(bf16x8, pk);
;     }
;     float mx = -INFINITY;
; #pragma unroll
;     for (int hb = 0; hb < 2; ++hb) {
;       bf16x8 vf[2][NDVT];
; #pragma unroll
;       for (int q = 0; q < 2; ++q)
; #pragma unroll
;         for (int d = 0; d < NDVT; ++d) {
;           const bft* vp = Vc + (d * 32 + r) * VS_STRIDE + (hb * 2 + q) * 16 + 4 * h2;
;           const u32x2 lo = *(const u32x2*)vp, hi = *(const u32x2*)(vp + 8);
;           const u32x4 pa4 = {lo.x, lo.y, hi.x, hi.y};
;           vf[q][d] = __builtin_bit_cast(bf16x8, pa4);
;         }
; #pragma unroll
.LBB0_559:
	s_or_b64 exec, exec, s[74:75]
	s_and_b64 vcc, exec, s[76:77]
	s_cbranch_vccnz .Lmla1_cold
	ds_read_b128 v[132:135], v155 offset:13312
	ds_read_b128 v[136:139], v155 offset:13344
	ds_read_b128 v[198:201], v155 offset:13376
	ds_read_b128 v[202:205], v155 offset:13408
	ds_read_b128 v[248:251], v155 offset:13440
	ds_read_b128 v[216:219], v155 offset:13472
	v_add_u32_e32 v244, 0x6800, v157
	v_add_u32_e32 v245, 0x7800, v157
	v_exp_f32_e32 v16, v16
	v_exp_f32_e32 v17, v17
	v_exp_f32_e32 v18, v18
	v_exp_f32_e32 v19, v19
	v_add_f32_e32 v163, v16, v18
	v_add_f32_e32 v210, v17, v19
	s_waitcnt lgkmcnt(5)
	v_mfma_f32_32x32x16_bf16 v[48:63], v[132:135], v[96:99], v[164:179]
	ds_read_b128 v[132:135], v155 offset:19968
	v_exp_f32_e32 v20, v20
	v_exp_f32_e32 v21, v21
	v_exp_f32_e32 v22, v22
	s_waitcnt lgkmcnt(5)
	v_mfma_f32_32x32x16_bf16 v[48:63], v[136:139], v[100:103], v[48:63]
	ds_read_b128 v[136:139], v155 offset:20000
	v_exp_f32_e32 v23, v23
	v_add_f32_e32 v163, v20, v163
	v_add_f32_e32 v210, v21, v210
	s_waitcnt lgkmcnt(5)
	v_mfma_f32_32x32x16_bf16 v[48:63], v[198:201], v[104:107], v[48:63]
	ds_read_b128 v[198:201], v155 offset:20032
	v_add_f32_e32 v163, v22, v163
	v_add_f32_e32 v210, v23, v210
	v_cvt_pk_bf16_f32 v180, v16, v17
	v_cvt_pk_bf16_f32 v181, v18, v19
	v_cvt_pk_bf16_f32 v182, v20, v21
	s_waitcnt lgkmcnt(5)
	v_mfma_f32_32x32x16_bf16 v[48:63], v[202:205], v[108:111], v[48:63]
	ds_read_b128 v[202:205], v155 offset:20064
	v_cvt_pk_bf16_f32 v183, v22, v23
	v_exp_f32_e32 v24, v24
	v_exp_f32_e32 v25, v25
	s_waitcnt lgkmcnt(5)
	v_mfma_f32_32x32x16_bf16 v[48:63], v[248:251], v[112:115], v[48:63]
	ds_read_b128 v[248:251], v155 offset:20096
	v_exp_f32_e32 v26, v26
	v_exp_f32_e32 v27, v27
	v_add_f32_e32 v163, v24, v163
	s_waitcnt lgkmcnt(5)
	v_mfma_f32_32x32x16_bf16 v[48:63], v[216:219], v[116:119], v[48:63]
	ds_read_b128 v[216:219], v155 offset:20128
	v_add_f32_e32 v210, v25, v210
	v_add_f32_e32 v163, v26, v163
	v_add_f32_e32 v210, v27, v210
	v_exp_f32_e32 v28, v28
	s_waitcnt lgkmcnt(5)
	v_mfma_f32_32x32x16_bf16 v[80:95], v[132:135], v[96:99], v[164:179]
	ds_read2_b64 v[132:135], v244 offset0:0 offset1:2
	v_exp_f32_e32 v29, v29
	v_exp_f32_e32 v30, v30
	v_exp_f32_e32 v31, v31
	s_waitcnt lgkmcnt(5)
	v_mfma_f32_32x32x16_bf16 v[80:95], v[136:139], v[100:103], v[80:95]
	ds_read2_b64 v[136:139], v245 offset0:32 offset1:34
	v_add_f32_e32 v163, v28, v163
	v_add_f32_e32 v210, v29, v210
	v_add_f32_e32 v163, v30, v163
	v_add_f32_e32 v210, v31, v210
	s_waitcnt lgkmcnt(5)
	v_mfma_f32_32x32x16_bf16 v[80:95], v[198:201], v[104:107], v[80:95]
	ds_read2_b64 v[198:201], v244 offset0:4 offset1:6
	v_cvt_pk_bf16_f32 v184, v24, v25
	v_cvt_pk_bf16_f32 v185, v26, v27
	v_cvt_pk_bf16_f32 v186, v28, v29
	v_cvt_pk_bf16_f32 v187, v30, v31
	v_exp_f32_e32 v64, v64
	s_waitcnt lgkmcnt(5)
	v_mfma_f32_32x32x16_bf16 v[80:95], v[202:205], v[108:111], v[80:95]
	ds_read2_b64 v[202:205], v245 offset0:36 offset1:38
	v_exp_f32_e32 v65, v65
	v_exp_f32_e32 v66, v66
	s_waitcnt lgkmcnt(5)
	v_mfma_f32_32x32x16_bf16 v[80:95], v[248:251], v[112:115], v[80:95]
	ds_read2_b64 v[248:251], v244 offset0:8 offset1:10
	v_exp_f32_e32 v67, v67
	v_add_f32_e32 v163, v64, v163
	v_add_f32_e32 v210, v65, v210
	s_waitcnt lgkmcnt(5)
	v_mfma_f32_32x32x16_bf16 v[80:95], v[216:219], v[116:119], v[80:95]
	ds_read2_b64 v[216:219], v245 offset0:40 offset1:42
	v_add_f32_e32 v163, v66, v163
	v_add_f32_e32 v210, v67, v210
	v_exp_f32_e32 v68, v68
	v_exp_f32_e32 v69, v69
	s_waitcnt lgkmcnt(5)
	v_mfma_f32_32x32x16_bf16 v[32:47], v[132:135], v[180:183], v[32:47]
	ds_read2_b64 v[132:135], v244 offset0:12 offset1:14
	v_exp_f32_e32 v70, v70
	v_exp_f32_e32 v71, v71
	s_waitcnt lgkmcnt(5)
	v_mfma_f32_32x32x16_bf16 v[0:15], v[136:139], v[180:183], v[0:15]
	ds_read2_b64 v[136:139], v245 offset0:44 offset1:46
	v_add_f32_e32 v163, v68, v163
	v_add_f32_e32 v210, v69, v210
	v_add_f32_e32 v163, v70, v163
	v_add_f32_e32 v210, v71, v210
	v_cvt_pk_bf16_f32 v188, v64, v65
	s_waitcnt lgkmcnt(5)
	v_mfma_f32_32x32x16_bf16 v[32:47], v[198:201], v[184:187], v[32:47]
	s_cmp_lt_u32 s68, s34
	s_cbranch_scc0 .Lm1i_ns
	s_and_b64 vcc, exec, s[8:9]
	s_cbranch_vccnz .Lm1i_w3
	s_waitcnt vmcnt(2)
	s_branch .Lm1i_wd

; DI unsigned pack2(float lo, float hi) { f2v_ f = {lo, hi}; b2v_ b = __builtin_convertvector(f, b2v_); return __builtin_bit_cast(unsigned, b); }
; #define MFMA32(a, b, c) __builtin_amdgcn_mfma_f32_32x32x16_bf16((a), (b), (c), 0, 0, 0)
; template <bool MLA, int DK, int DV>
; __device__ __forceinline__ void attn_core(const Params& p, int b, int h, int map, int q0, int nt, char* smem,
;                                           f32x16 (&o)[DV / 32], float& lout) {
;     ...
;     bf16x8 pb[4];
; #pragma unroll
;     for (int kb = 0; kb < 4; ++kb) {
;       const int sub = kb >> 1, s8 = (kb & 1) * 8;
;       u32x4 pk;
;       pk.x = pack2(cur_[sub][s8 + 0], cur_[sub][s8 + 1]);
;       pk.y = pack2(cur_[sub][s8 + 2], cur_[sub][s8 + 3]);
;       pk.z = pack2(cur_[sub][s8 + 4], cur_[sub][s8 + 5]);
;       pk.w = pack2(cur_[sub][s8 + 6], cur_[sub][s8 + 7]);
;       pb[kb] = __builtin_bit_cast(bf16x8, pk);
;     }
;     float mx = -INFINITY;
; #pragma unroll
;     for (int hb = 0; hb < 2; ++hb) {
;       bf16x8 vf[2][NDVT];
; #pragma unroll
;       for (int q = 0; q < 2; ++q)
; #pragma unroll
;         for (int d = 0; d < NDVT; ++d) {
;           const bft* vp = Vc + (d * 32 + r) * VS_STRIDE + (hb * 2 + q) * 16 + 4 * h2;
;           const u32x2 lo = *(const u32x2*)vp, hi = *(const u32x2*)(vp + 8);
;           const u32x4 pa4 = {lo.x, lo.y, hi.x, hi.y};
;           vf[q][d] = __builtin_bit_cast(bf16x8, pa4);
;         }
; #pragma unroll
;       for (int q = 0; q < 2; ++q) {
;         const int kb = hb * 2 + q;
; #pragma unroll
;         for (int d = 0; d < NDVT; ++d) o[d] = MFMA32(vf[q][d], pb[kb], o[d]);
; #pragma unroll
;         for (int i = 0; i < 8; ++i) mx = fmaxf(mx, nxt_[kb >> 1][(kb & 1) * 8 + i]);
;       }
;     }
;     if (has1) {
;       mx *= sc;
;       if (__any(mx > mrun + 12.f)) {
;         mx = fmaxf(mx, __shfl_xor(mx, 32));
;         const float mnew = fmaxf(mrun, mx);
;         const float alpha = __builtin_amdgcn_exp2f(mrun - mnew);
;         mrun = mnew;
;         lrun *= alpha;
; #pragma unroll
;         for (int d = 0; d < NDVT; ++d)
; #pragma unroll
;           for (int i = 0; i < 16; ++i) o[d][i] *= alpha;
;       }
.Lm1i_d:
	s_or_b64 exec, exec, s[74:75]
	s_nop 3
	v_cvt_pk_bf16_f32 v189, v66, v67
	v_cvt_pk_bf16_f32 v190, v68, v69
	v_cvt_pk_bf16_f32 v191, v70, v71
	v_exp_f32_e32 v72, v72
	s_waitcnt lgkmcnt(4)
	v_mfma_f32_32x32x16_bf16 v[0:15], v[202:205], v[184:187], v[0:15]
	v_exp_f32_e32 v73, v73
	v_exp_f32_e32 v74, v74
	v_exp_f32_e32 v75, v75
	s_waitcnt lgkmcnt(3)
	v_mfma_f32_32x32x16_bf16 v[32:47], v[248:251], v[188:191], v[32:47]
	v_add_f32_e32 v163, v72, v163
	v_add_f32_e32 v210, v73, v210
	v_add_f32_e32 v163, v74, v163
	v_add_f32_e32 v210, v75, v210
	s_waitcnt lgkmcnt(2)
	v_mfma_f32_32x32x16_bf16 v[0:15], v[216:219], v[188:191], v[0:15]
	v_exp_f32_e32 v76, v76
	v_exp_f32_e32 v77, v77
	v_exp_f32_e32 v78, v78
	v_exp_f32_e32 v79, v79
	v_add_f32_e32 v163, v76, v163
	v_add_f32_e32 v210, v77, v210
	v_add_f32_e32 v163, v78, v163
	v_add_f32_e32 v210, v79, v210
	v_cvt_pk_bf16_f32 v192, v72, v73
	v_cvt_pk_bf16_f32 v193, v74, v75
	v_cvt_pk_bf16_f32 v194, v76, v77
	v_cvt_pk_bf16_f32 v195, v78, v79
	s_waitcnt lgkmcnt(1)
	s_nop 0
	v_mfma_f32_32x32x16_bf16 v[32:47], v[132:135], v[192:195], v[32:47]
	s_waitcnt lgkmcnt(0)
	v_mfma_f32_32x32x16_bf16 v[0:15], v[136:139], v[192:195], v[0:15]
	v_add_f32_e32 v163, v163, v210
	v_add_f32_e32 v149, v149, v163
	s_andn2_b64 s[16:17], exec, s[70:71]
	v_cmp_lt_f32_e32 vcc, 0x45800000, v163
	s_cbranch_vccz .Lmla1_post
	v_max3_f32 v163, v16, v17, v18
	v_max3_f32 v163, v163, v19, v20
	v_max3_f32 v163, v163, v21, v22
	v_max3_f32 v163, v163, v23, v24
	v_max3_f32 v163, v163, v25, v26
	v_max3_f32 v163, v163, v27, v28
	v_max3_f32 v163, v163, v29, v30
	v_max3_f32 v163, v163, v31, v64
	v_max3_f32 v163, v163, v65, v66
	v_max3_f32 v163, v163, v67, v68
	v_max3_f32 v163, v163, v69, v70
	v_max3_f32 v163, v163, v71, v72
	v_max3_f32 v163, v163, v73, v74
	v_max3_f32 v163, v163, v75, v76
	v_max3_f32 v163, v163, v77, v78
	v_max_f32_e32 v163, v163, v79
	ds_bpermute_b32 v210, v156, v163
	s_waitcnt lgkmcnt(0)
	v_max_f32_e32 v163, v163, v210
	v_frexp_exp_i32_f32_e32 v210, v163
	v_max_i32_e32 v210, 0, v210
	v_sub_u32_e32 v247, 0, v210
	v_ldexp_f32 v247, 1.0, v247
	v_cvt_f32_i32_e32 v210, v210
	v_mul_f32_e32 v149, v149, v247
	v_mul_f32_e32 v32, v32, v247
	v_mul_f32_e32 v33, v33, v247
	v_mul_f32_e32 v34, v34, v247
	v_mul_f32_e32 v35, v35, v247
	v_mul_f32_e32 v36, v36, v247
	v_mul_f32_e32 v37, v37, v247
	v_mul_f32_e32 v38, v38, v247
	v_mul_f32_e32 v39, v39, v247
	v_mul_f32_e32 v40, v40, v247
	v_mul_f32_e32 v41, v41, v247
	v_mul_f32_e32 v42, v42, v247
	v_mul_f32_e32 v43, v43, v247
	v_mul_f32_e32 v44, v44, v247
	v_mul_f32_e32 v45, v45, v247
	v_mul_f32_e32 v46, v46, v247
	v_mul_f32_e32 v47, v47, v247
	v_mul_f32_e32 v0, v0, v247
	v_mul_f32_e32 v1, v1, v247
	v_mul_f32_e32 v2, v2, v247
	v_mul_f32_e32 v3, v3, v247
	v_mul_f32_e32 v4, v4, v247
	v_mul_f32_e32 v5, v5, v247
	v_mul_f32_e32 v6, v6, v247
	v_mul_f32_e32 v7, v7, v247
	v_mul_f32_e32 v8, v8, v247
	v_mul_f32_e32 v9, v9, v247
	v_mul_f32_e32 v10, v10, v247
	v_mul_f32_e32 v11, v11, v247
	v_mul_f32_e32 v12, v12, v247
	v_mul_f32_e32 v13, v13, v247
	v_mul_f32_e32 v14, v14, v247
	v_mul_f32_e32 v15, v15, v247
	v_sub_f32_e32 v164, v164, v210
	v_sub_f32_e32 v165, v165, v210
	v_sub_f32_e32 v166, v166, v210
	v_sub_f32_e32 v167, v167, v210
	v_sub_f32_e32 v168, v168, v210
	v_sub_f32_e32 v169, v169, v210
	v_sub_f32_e32 v170, v170, v210
	v_sub_f32_e32 v171, v171, v210
	v_sub_f32_e32 v172, v172, v210
	v_sub_f32_e32 v173, v173, v210
	v_sub_f32_e32 v174, v174, v210
	v_sub_f32_e32 v175, v175, v210
	v_sub_f32_e32 v176, v176, v210
	v_sub_f32_e32 v177, v177, v210
	v_sub_f32_e32 v178, v178, v210
	v_sub_f32_e32 v179, v179, v210
	v_sub_f32_e32 v48, v48, v210
	v_sub_f32_e32 v49, v49, v210
	v_sub_f32_e32 v50, v50, v210
	v_sub_f32_e32 v51, v51, v210
	v_sub_f32_e32 v52, v52, v210
	v_sub_f32_e32 v53, v53, v210
	v_sub_f32_e32 v54, v54, v210
	v_sub_f32_e32 v55, v55, v210
	v_sub_f32_e32 v56, v56, v210
	v_sub_f32_e32 v57, v57, v210
	v_sub_f32_e32 v58, v58, v210
	v_sub_f32_e32 v59, v59, v210
	v_sub_f32_e32 v60, v60, v210
	v_sub_f32_e32 v61, v61, v210
	v_sub_f32_e32 v62, v62, v210
	v_sub_f32_e32 v63, v63, v210
	v_sub_f32_e32 v80, v80, v210
	v_sub_f32_e32 v81, v81, v210
	v_sub_f32_e32 v82, v82, v210
	v_sub_f32_e32 v83, v83, v210
	v_sub_f32_e32 v84, v84, v210
	v_sub_f32_e32 v85, v85, v210
	v_sub_f32_e32 v86, v86, v210
	v_sub_f32_e32 v87, v87, v210
	v_sub_f32_e32 v88, v88, v210
	v_sub_f32_e32 v89, v89, v210
	v_sub_f32_e32 v90, v90, v210
	v_sub_f32_e32 v91, v91, v210
	v_sub_f32_e32 v92, v92, v210
	v_sub_f32_e32 v93, v93, v210
	v_sub_f32_e32 v94, v94, v210
	v_sub_f32_e32 v95, v95, v210
	v_add_f32_e32 v162, v162, v210
	s_branch .Lmla1_post

; template <bool MLA, int DK, int DV>
; __device__ __forceinline__ void attn_core(const Params& p, int b, int h, int map, int q0, int nt, char* smem,
;                                           f32x16 (&o)[DV / 32], float& lout) {
;     ...
;         for (int i = 0; i < 16; ++i) nxt_[sub][i] = 0.f;
;       constexpr int NM = 2 * NKS;
;       bf16x8 kf[NM];
; #pragma unroll
;       for (int j = 0; j < NM; ++j) kf[j] = *(const bf16x8*)(Kn + ((j / NKS) * 32 + r) * KS_STRIDE + (j % NKS) * 16 + h2 * 8);
; #pragma unroll
;       for (int j = 0; j < NM; ++j) {
;         nxt_[j / NKS] = MFMA32(kf[j], qf[j % NKS], nxt_[j / NKS]);
; #pragma unroll
;         for (int e_ = j * 32 / NM; e_ < (j + 1) * 32 / NM; ++e_) {
;           const float x_ = __builtin_amdgcn_exp2f(fmaf(cur_[e_ >> 4][e_ & 15], sc, -mrun));
;           cur_[e_ >> 4][e_ & 15] = x_; psum += x_;
;         }
;       }
;       __builtin_amdgcn_sched_group_barrier(0x100, NM, 0);
; #pragma unroll
;       for (int j = 0; j < NM; ++j) {
;         __builtin_amdgcn_sched_group_barrier(0x008, 1, 0);
;         __builtin_amdgcn_sched_group_barrier(0x002, 96 / NM, 0);
;       }
;     } else {
; #pragma unroll
;       for (int sub = 0; sub < 2; ++sub)
; #pragma unroll
;         for (int i = 0; i < 16; ++i) { const float x_ = __builtin_amdgcn_exp2f(fmaf(cur_[sub][i], sc, -mrun)); cur_[sub][i] = x_; psum += x_; }
;     }
;     lrun += psum;
;     bf16x8 pb[4];
; #pragma unroll
;     for (int kb = 0; kb < 4; ++kb) {
;       const int sub = kb >> 1, s8 = (kb & 1) * 8;
;       u32x4 pk;
;       pk.x = pack2(cur_[sub][s8 + 0], cur_[sub][s8 + 1]);
;       pk.y = pack2(cur_[sub][s8 + 2], cur_[sub][s8 + 3]);
;       pk.z = pack2(cur_[sub][s8 + 4], cur_[sub][s8 + 5]);
;       pk.w = pack2(cur_[sub][s8 + 6], cur_[sub][s8 + 7]);
;       pb[kb] = __builtin_bit_cast(bf16x8, pk);
;     }
;     float mx = -INFINITY;
; #pragma unroll
;     for (int hb = 0; hb < 2; ++hb) {
;       bf16x8 vf[2][NDVT];
; #pragma unroll
;       for (int q = 0; q < 2; ++q)
; #pragma unroll
;         for (int d = 0; d < NDVT; ++d) {
;           const bft* vp = Vc + (d * 32 + r) * VS_STRIDE + (hb * 2 + q) * 16 + 4 * h2;
;           const u32x2 lo = *(const u32x2*)vp, hi = *(const u32x2*)(vp + 8);
;           const u32x4 pa4 = {lo.x, lo.y, hi.x, hi.y};
;           vf[q][d] = __builtin_bit_cast(bf16x8, pa4);
;         }
; #pragma unroll
.LBB0_590:
	s_or_b64 exec, exec, s[74:75]
	s_and_b64 vcc, exec, s[50:51]
	s_cbranch_vccnz .Lmla2_cold
	ds_read_b128 v[132:135], v155 offset:0
	ds_read_b128 v[136:139], v155 offset:32
	ds_read_b128 v[198:201], v155 offset:64
	ds_read_b128 v[202:205], v155 offset:96
	ds_read_b128 v[248:251], v155 offset:128
	ds_read_b128 v[216:219], v155 offset:160
	v_add_u32_e32 v244, 0x8800, v157
	v_add_u32_e32 v245, 0x9800, v157
	v_exp_f32_e32 v48, v48
	v_exp_f32_e32 v49, v49
	v_exp_f32_e32 v50, v50
	v_exp_f32_e32 v51, v51
	v_add_f32_e32 v163, v48, v50
	v_add_f32_e32 v210, v49, v51
	s_waitcnt lgkmcnt(5)
	v_mfma_f32_32x32x16_bf16 v[16:31], v[132:135], v[96:99], v[164:179]
	ds_read_b128 v[132:135], v155 offset:6656
	v_exp_f32_e32 v52, v52
	v_exp_f32_e32 v53, v53
	v_exp_f32_e32 v54, v54
	s_waitcnt lgkmcnt(5)
	v_mfma_f32_32x32x16_bf16 v[16:31], v[136:139], v[100:103], v[16:31]
	ds_read_b128 v[136:139], v155 offset:6688
	v_exp_f32_e32 v55, v55
	v_add_f32_e32 v163, v52, v163
	v_add_f32_e32 v210, v53, v210
	s_waitcnt lgkmcnt(5)
	v_mfma_f32_32x32x16_bf16 v[16:31], v[198:201], v[104:107], v[16:31]
	ds_read_b128 v[198:201], v155 offset:6720
	v_add_f32_e32 v163, v54, v163
	v_add_f32_e32 v210, v55, v210
	v_cvt_pk_bf16_f32 v180, v48, v49
	v_cvt_pk_bf16_f32 v181, v50, v51
	v_cvt_pk_bf16_f32 v182, v52, v53
	s_waitcnt lgkmcnt(5)
	v_mfma_f32_32x32x16_bf16 v[16:31], v[202:205], v[108:111], v[16:31]
	ds_read_b128 v[202:205], v155 offset:6752
	v_cvt_pk_bf16_f32 v183, v54, v55
	v_exp_f32_e32 v56, v56
	v_exp_f32_e32 v57, v57
	s_waitcnt lgkmcnt(5)
	v_mfma_f32_32x32x16_bf16 v[16:31], v[248:251], v[112:115], v[16:31]
	ds_read_b128 v[248:251], v155 offset:6784
	v_exp_f32_e32 v58, v58
	v_exp_f32_e32 v59, v59
	v_add_f32_e32 v163, v56, v163
	s_waitcnt lgkmcnt(5)
	v_mfma_f32_32x32x16_bf16 v[16:31], v[216:219], v[116:119], v[16:31]
	ds_read_b128 v[216:219], v155 offset:6816
	v_add_f32_e32 v210, v57, v210
	v_add_f32_e32 v163, v58, v163
	v_add_f32_e32 v210, v59, v210
	v_exp_f32_e32 v60, v60
	s_waitcnt lgkmcnt(5)
	v_mfma_f32_32x32x16_bf16 v[64:79], v[132:135], v[96:99], v[164:179]
	ds_read2_b64 v[132:135], v244 offset0:64 offset1:66
	v_exp_f32_e32 v61, v61
	v_exp_f32_e32 v62, v62
	v_exp_f32_e32 v63, v63
	s_waitcnt lgkmcnt(5)
	v_mfma_f32_32x32x16_bf16 v[64:79], v[136:139], v[100:103], v[64:79]
	ds_read2_b64 v[136:139], v245 offset0:96 offset1:98
	v_add_f32_e32 v163, v60, v163
	v_add_f32_e32 v210, v61, v210
	v_add_f32_e32 v163, v62, v163
	v_add_f32_e32 v210, v63, v210
	s_waitcnt lgkmcnt(5)
	v_mfma_f32_32x32x16_bf16 v[64:79], v[198:201], v[104:107], v[64:79]
	ds_read2_b64 v[198:201], v244 offset0:68 offset1:70
	v_cvt_pk_bf16_f32 v184, v56, v57
	v_cvt_pk_bf16_f32 v185, v58, v59
	v_cvt_pk_bf16_f32 v186, v60, v61
	v_cvt_pk_bf16_f32 v187, v62, v63
	v_exp_f32_e32 v80, v80
	s_waitcnt lgkmcnt(5)
	v_mfma_f32_32x32x16_bf16 v[64:79], v[202:205], v[108:111], v[64:79]
	ds_read2_b64 v[202:205], v245 offset0:100 offset1:102
	v_exp_f32_e32 v81, v81
	v_exp_f32_e32 v82, v82
	s_waitcnt lgkmcnt(5)
	v_mfma_f32_32x32x16_bf16 v[64:79], v[248:251], v[112:115], v[64:79]
	ds_read2_b64 v[248:251], v244 offset0:72 offset1:74
	v_exp_f32_e32 v83, v83
	v_add_f32_e32 v163, v80, v163
	v_add_f32_e32 v210, v81, v210
	s_waitcnt lgkmcnt(5)
	v_mfma_f32_32x32x16_bf16 v[64:79], v[216:219], v[116:119], v[64:79]
	ds_read2_b64 v[216:219], v245 offset0:104 offset1:106
	v_add_f32_e32 v163, v82, v163
	v_add_f32_e32 v210, v83, v210
	v_exp_f32_e32 v84, v84
	v_exp_f32_e32 v85, v85
	s_waitcnt lgkmcnt(5)
	v_mfma_f32_32x32x16_bf16 v[32:47], v[132:135], v[180:183], v[32:47]
	ds_read2_b64 v[132:135], v244 offset0:76 offset1:78
	v_exp_f32_e32 v86, v86
	v_exp_f32_e32 v87, v87
	s_waitcnt lgkmcnt(5)
	v_mfma_f32_32x32x16_bf16 v[0:15], v[136:139], v[180:183], v[0:15]
	ds_read2_b64 v[136:139], v245 offset0:108 offset1:110
	v_add_f32_e32 v163, v84, v163
	v_add_f32_e32 v210, v85, v210
	v_add_f32_e32 v163, v86, v163
	v_add_f32_e32 v210, v87, v210
	v_cvt_pk_bf16_f32 v188, v80, v81
	s_waitcnt lgkmcnt(5)
	v_mfma_f32_32x32x16_bf16 v[32:47], v[198:201], v[184:187], v[32:47]
	s_add_i32 s60, s68, 1
	s_cmp_lt_u32 s60, s34
	s_cbranch_scc0 .Lm2i_ns
	s_and_b64 vcc, exec, s[8:9]
	s_cbranch_vccnz .Lm2i_w3
	s_waitcnt vmcnt(2)
	s_branch .Lm2i_wd

; DI unsigned pack2(float lo, float hi) { f2v_ f = {lo, hi}; b2v_ b = __builtin_convertvector(f, b2v_); return __builtin_bit_cast(unsigned, b); }
; #define MFMA32(a, b, c) __builtin_amdgcn_mfma_f32_32x32x16_bf16((a), (b), (c), 0, 0, 0)
; template <bool MLA, int DK, int DV>
; __device__ __forceinline__ void attn_core(const Params& p, int b, int h, int map, int q0, int nt, char* smem,
;                                           f32x16 (&o)[DV / 32], float& lout) {
;     ...
;     bf16x8 pb[4];
; #pragma unroll
;     for (int kb = 0; kb < 4; ++kb) {
;       const int sub = kb >> 1, s8 = (kb & 1) * 8;
;       u32x4 pk;
;       pk.x = pack2(cur_[sub][s8 + 0], cur_[sub][s8 + 1]);
;       pk.y = pack2(cur_[sub][s8 + 2], cur_[sub][s8 + 3]);
;       pk.z = pack2(cur_[sub][s8 + 4], cur_[sub][s8 + 5]);
;       pk.w = pack2(cur_[sub][s8 + 6], cur_[sub][s8 + 7]);
;       pb[kb] = __builtin_bit_cast(bf16x8, pk);
;     }
;     float mx = -INFINITY;
; #pragma unroll
;     for (int hb = 0; hb < 2; ++hb) {
;       bf16x8 vf[2][NDVT];
; #pragma unroll
;       for (int q = 0; q < 2; ++q)
; #pragma unroll
;         for (int d = 0; d < NDVT; ++d) {
;           const bft* vp = Vc + (d * 32 + r) * VS_STRIDE + (hb * 2 + q) * 16 + 4 * h2;
;           const u32x2 lo = *(const u32x2*)vp, hi = *(const u32x2*)(vp + 8);
;           const u32x4 pa4 = {lo.x, lo.y, hi.x, hi.y};
;           vf[q][d] = __builtin_bit_cast(bf16x8, pa4);
;         }
; #pragma unroll
;       for (int q = 0; q < 2; ++q) {
;         const int kb = hb * 2 + q;
; #pragma unroll
;         for (int d = 0; d < NDVT; ++d) o[d] = MFMA32(vf[q][d], pb[kb], o[d]);
; #pragma unroll
;         for (int i = 0; i < 8; ++i) mx = fmaxf(mx, nxt_[kb >> 1][(kb & 1) * 8 + i]);
;       }
;     }
;     if (has1) {
;       mx *= sc;
;       if (__any(mx > mrun + 12.f)) {
;         mx = fmaxf(mx, __shfl_xor(mx, 32));
;         const float mnew = fmaxf(mrun, mx);
;         const float alpha = __builtin_amdgcn_exp2f(mrun - mnew);
;         mrun = mnew;
;         lrun *= alpha;
; #pragma unroll
;         for (int d = 0; d < NDVT; ++d)
; #pragma unroll
;           for (int i = 0; i < 16; ++i) o[d][i] *= alpha;
;       }
.Lm2i_d:
	s_or_b64 exec, exec, s[74:75]
	s_nop 3
	v_cvt_pk_bf16_f32 v189, v82, v83
	v_cvt_pk_bf16_f32 v190, v84, v85
	v_cvt_pk_bf16_f32 v191, v86, v87
	v_exp_f32_e32 v88, v88
	s_waitcnt lgkmcnt(4)
	v_mfma_f32_32x32x16_bf16 v[0:15], v[202:205], v[184:187], v[0:15]
	v_exp_f32_e32 v89, v89
	v_exp_f32_e32 v90, v90
	v_exp_f32_e32 v91, v91
	s_waitcnt lgkmcnt(3)
	v_mfma_f32_32x32x16_bf16 v[32:47], v[248:251], v[188:191], v[32:47]
	v_add_f32_e32 v163, v88, v163
	v_add_f32_e32 v210, v89, v210
	v_add_f32_e32 v163, v90, v163
	v_add_f32_e32 v210, v91, v210
	s_waitcnt lgkmcnt(2)
	v_mfma_f32_32x32x16_bf16 v[0:15], v[216:219], v[188:191], v[0:15]
	v_exp_f32_e32 v92, v92
	v_exp_f32_e32 v93, v93
	v_exp_f32_e32 v94, v94
	v_exp_f32_e32 v95, v95
	v_add_f32_e32 v163, v92, v163
	v_add_f32_e32 v210, v93, v210
	v_add_f32_e32 v163, v94, v163
	v_add_f32_e32 v210, v95, v210
	v_cvt_pk_bf16_f32 v192, v88, v89
	v_cvt_pk_bf16_f32 v193, v90, v91
	v_cvt_pk_bf16_f32 v194, v92, v93
	v_cvt_pk_bf16_f32 v195, v94, v95
	s_waitcnt lgkmcnt(1)
	s_nop 0
	v_mfma_f32_32x32x16_bf16 v[32:47], v[132:135], v[192:195], v[32:47]
	s_waitcnt lgkmcnt(0)
	v_mfma_f32_32x32x16_bf16 v[0:15], v[136:139], v[192:195], v[0:15]
	v_add_f32_e32 v163, v163, v210
	v_add_f32_e32 v149, v149, v163
	v_cmp_lt_f32_e32 vcc, 0x45800000, v163
	s_cbranch_vccz .Lmla2_post
	v_max3_f32 v163, v48, v49, v50
	v_max3_f32 v163, v163, v51, v52
	v_max3_f32 v163, v163, v53, v54
	v_max3_f32 v163, v163, v55, v56
	v_max3_f32 v163, v163, v57, v58
	v_max3_f32 v163, v163, v59, v60
	v_max3_f32 v163, v163, v61, v62
	v_max3_f32 v163, v163, v63, v80
	v_max3_f32 v163, v163, v81, v82
	v_max3_f32 v163, v163, v83, v84
	v_max3_f32 v163, v163, v85, v86
	v_max3_f32 v163, v163, v87, v88
	v_max3_f32 v163, v163, v89, v90
	v_max3_f32 v163, v163, v91, v92
	v_max3_f32 v163, v163, v93, v94
	v_max_f32_e32 v163, v163, v95
	ds_bpermute_b32 v210, v156, v163
	s_waitcnt lgkmcnt(0)
	v_max_f32_e32 v163, v163, v210
	v_frexp_exp_i32_f32_e32 v210, v163
	v_max_i32_e32 v210, 0, v210
	v_sub_u32_e32 v247, 0, v210
	v_ldexp_f32 v247, 1.0, v247
	v_cvt_f32_i32_e32 v210, v210
	v_mul_f32_e32 v149, v149, v247
	v_mul_f32_e32 v32, v32, v247
	v_mul_f32_e32 v33, v33, v247
	v_mul_f32_e32 v34, v34, v247
	v_mul_f32_e32 v35, v35, v247
	v_mul_f32_e32 v36, v36, v247
	v_mul_f32_e32 v37, v37, v247
	v_mul_f32_e32 v38, v38, v247
	v_mul_f32_e32 v39, v39, v247
	v_mul_f32_e32 v40, v40, v247
	v_mul_f32_e32 v41, v41, v247
	v_mul_f32_e32 v42, v42, v247
	v_mul_f32_e32 v43, v43, v247
	v_mul_f32_e32 v44, v44, v247
	v_mul_f32_e32 v45, v45, v247
	v_mul_f32_e32 v46, v46, v247
	v_mul_f32_e32 v47, v47, v247
	v_mul_f32_e32 v0, v0, v247
	v_mul_f32_e32 v1, v1, v247
	v_mul_f32_e32 v2, v2, v247
	v_mul_f32_e32 v3, v3, v247
	v_mul_f32_e32 v4, v4, v247
	v_mul_f32_e32 v5, v5, v247
	v_mul_f32_e32 v6, v6, v247
	v_mul_f32_e32 v7, v7, v247
	v_mul_f32_e32 v8, v8, v247
	v_mul_f32_e32 v9, v9, v247
	v_mul_f32_e32 v10, v10, v247
	v_mul_f32_e32 v11, v11, v247
	v_mul_f32_e32 v12, v12, v247
	v_mul_f32_e32 v13, v13, v247
	v_mul_f32_e32 v14, v14, v247
	v_mul_f32_e32 v15, v15, v247
	v_sub_f32_e32 v164, v164, v210
	v_sub_f32_e32 v165, v165, v210
	v_sub_f32_e32 v166, v166, v210
	v_sub_f32_e32 v167, v167, v210
	v_sub_f32_e32 v168, v168, v210
	v_sub_f32_e32 v169, v169, v210
	v_sub_f32_e32 v170, v170, v210
	v_sub_f32_e32 v171, v171, v210
	v_sub_f32_e32 v172, v172, v210
	v_sub_f32_e32 v173, v173, v210
	v_sub_f32_e32 v174, v174, v210
	v_sub_f32_e32 v175, v175, v210
	v_sub_f32_e32 v176, v176, v210
	v_sub_f32_e32 v177, v177, v210
	v_sub_f32_e32 v178, v178, v210
	v_sub_f32_e32 v179, v179, v210
	v_sub_f32_e32 v16, v16, v210
	v_sub_f32_e32 v17, v17, v210
	v_sub_f32_e32 v18, v18, v210
	v_sub_f32_e32 v19, v19, v210
	v_sub_f32_e32 v20, v20, v210
	v_sub_f32_e32 v21, v21, v210
	v_sub_f32_e32 v22, v22, v210
	v_sub_f32_e32 v23, v23, v210
	v_sub_f32_e32 v24, v24, v210
	v_sub_f32_e32 v25, v25, v210
	v_sub_f32_e32 v26, v26, v210
	v_sub_f32_e32 v27, v27, v210
	v_sub_f32_e32 v28, v28, v210
	v_sub_f32_e32 v29, v29, v210
	v_sub_f32_e32 v30, v30, v210
	v_sub_f32_e32 v31, v31, v210
	v_sub_f32_e32 v64, v64, v210
	v_sub_f32_e32 v65, v65, v210
	v_sub_f32_e32 v66, v66, v210
	v_sub_f32_e32 v67, v67, v210
	v_sub_f32_e32 v68, v68, v210
	v_sub_f32_e32 v69, v69, v210
	v_sub_f32_e32 v70, v70, v210
	v_sub_f32_e32 v71, v71, v210
	v_sub_f32_e32 v72, v72, v210
	v_sub_f32_e32 v73, v73, v210
	v_sub_f32_e32 v74, v74, v210
	v_sub_f32_e32 v75, v75, v210
	v_sub_f32_e32 v76, v76, v210
	v_sub_f32_e32 v77, v77, v210
	v_sub_f32_e32 v78, v78, v210
	v_sub_f32_e32 v79, v79, v210
	v_add_f32_e32 v162, v162, v210
	s_branch .Lmla2_post
